# fsub + grid barriers 2..9 rewritten (XCD arrival counter, single global arrival word polled by all, same fences)
# speedup vs baseline: 1.0311x; 1.0052x over previous
; __device__ __forceinline__ unsigned xb_ld(unsigned* p)              { return __hip_atomic_load(p, __ATOMIC_RELAXED, __HIP_MEMORY_SCOPE_AGENT); }
; __device__ __forceinline__ unsigned xb_add(unsigned* p, unsigned v) { return __hip_atomic_fetch_add(p, v, __ATOMIC_RELAXED, __HIP_MEMORY_SCOPE_AGENT); }
; #define XB_SPIN(cond, bar) do { unsigned _sp = 0; while (cond) { __builtin_amdgcn_s_sleep(1); \
;     if ((++_sp & 255u) == 0u) { if (xb_ld(&(bar)[XB_TMO])) break; if (_sp > XB_SPIN_CAP) { atomicAdd(&(bar)[XB_TMO], 1u); break; } } } } while (0)
; #define PH_SYNC(k) do { if (p.ph_lo < (k) && (k) < p.ph_hi) xcd_barrier(xb); } while (0)
; __device__ __forceinline__ void xcd_barrier(const XcdBarrier& b) {
;     asm volatile("s_waitcnt vmcnt(0)" ::: "memory");
;     __syncthreads();
;     if (threadIdx.x == 0) {
;         unsigned* bar = b.bar;
;         __builtin_amdgcn_s_waitcnt(0);
;         unsigned nloc = b.st[0], nx = b.st[1];
;         if (nloc == 0u) { xcd_barrier_complete(bar, b.x, nloc, nx); b.st[0] = nloc; b.st[1] = nx; }
;         const unsigned old = xb_add(&bar[XB_XSUB(b.x)], 1u);
;         const unsigned gen = old / nloc;
;         if (old + 1u == (gen + 1u) * nloc) {
;             __builtin_amdgcn_fence(__ATOMIC_RELEASE, "agent");
;             asm volatile("s_waitcnt vmcnt(0)" ::: "memory");
;             const unsigned og = xb_add(&bar[XB_TOP], 1u);
;             const unsigned tg = og / nx;
;             if (og + 1u == (tg + 1u) * nx) xb_add(&bar[XB_TOPGEN], 1u);
;             else XB_SPIN(xb_ld(&bar[XB_TOPGEN]) == tg, bar);
;             __builtin_amdgcn_fence(__ATOMIC_ACQUIRE, "agent");
;             xb_add(&bar[XB_XGEN(b.x)], 1u);
;             asm volatile("s_waitcnt vmcnt(0)" ::: "memory");
;         } else {
;             XB_SPIN(xb_ld(&bar[XB_XGEN(b.x)]) == gen, bar);
;             __builtin_amdgcn_fence(__ATOMIC_ACQUIRE, "agent");
;             asm volatile("s_waitcnt vmcnt(0)" ::: "memory");
;         }
;     }
;     __syncthreads();
; }
; __global__ void __launch_bounds__(512, 2) mega(Params p) {
;     ...
;     PH_SYNC(2);
;     if (PH_ON(2)) dn_prep(p, L);
;     PH_SYNC(3);
.LBB0_133:
	s_cmp_gt_i32 s85, 2
	s_cselect_b64 s[2:3], -1, 0
	s_and_b64 s[0:1], s[4:5], s[2:3]
	s_andn2_b64 vcc, exec, s[0:1]
	s_cbranch_vccnz .LBB0_187
	s_waitcnt vmcnt(0) lgkmcnt(0)
	s_barrier
	s_mov_b64 s[4:5], exec
	v_readlane_b32 s0, v248, 1
	v_readlane_b32 s1, v248, 2
	s_and_b64 s[0:1], s[4:5], s[0:1]
	s_mov_b64 exec, s[0:1]
	s_cbranch_execz .LBB0_186
	s_add_i32 s0, 0, 0x20000
	v_mov_b32_e32 v0, s0
	ds_read_b32 v2, v0
	ds_read_b32 v3, v0 offset:4
	v_readlane_b32 s6, v248, 5
	v_readlane_b32 s8, v248, 3
	v_readlane_b32 s9, v248, 4
	s_lshl_b32 s6, s6, 8
	s_add_u32 s6, s8, s6
	s_addc_u32 s7, s9, 0
	v_mov_b32_e32 v4, 0x1000
	v_mov_b32_e32 v1, 1
	s_nop 4
	global_atomic_add v5, v4, v1, s[6:7] offset:1024 sc0
	s_waitcnt vmcnt(0) lgkmcnt(0)
	v_readfirstlane_b32 s10, v5
	v_readfirstlane_b32 s11, v2
	v_readfirstlane_b32 s12, v3
	s_nop 3
	s_add_u32 s10, s10, 1
	s_mul_i32 s11, s11, 2
	s_mul_i32 s12, s12, 2
	s_cmp_lg_u32 s10, s11
	s_cbranch_scc1 .Lnb_wait_1
	buffer_wbl2 sc1
	s_waitcnt vmcnt(0)
	v_mov_b32_e32 v4, 0xbed7000
	global_atomic_add v4, v1, s[50:51] offset:1024
.Lnb_wait_1:
	v_mov_b32_e32 v4, 0xbed7400
	s_mov_b32 s13, 0
.Lnb_spin_1:
	global_load_dword v5, v4, s[50:51] sc1
	s_waitcnt vmcnt(0)
	v_readfirstlane_b32 s10, v5
	s_nop 3
	s_cmp_ge_u32 s10, s12
	s_cbranch_scc1 .Lnb_done_1
	s_sleep 1
	s_add_u32 s13, s13, 1
	s_cmp_lt_u32 s13, 0x40000
	s_cbranch_scc1 .Lnb_spin_1
.Lnb_done_1:
	buffer_inv sc1
	s_waitcnt vmcnt(0)

; __device__ __forceinline__ unsigned xb_ld(unsigned* p)              { return __hip_atomic_load(p, __ATOMIC_RELAXED, __HIP_MEMORY_SCOPE_AGENT); }
; __device__ __forceinline__ unsigned xb_add(unsigned* p, unsigned v) { return __hip_atomic_fetch_add(p, v, __ATOMIC_RELAXED, __HIP_MEMORY_SCOPE_AGENT); }
; #define XB_SPIN(cond, bar) do { unsigned _sp = 0; while (cond) { __builtin_amdgcn_s_sleep(1); \
;     if ((++_sp & 255u) == 0u) { if (xb_ld(&(bar)[XB_TMO])) break; if (_sp > XB_SPIN_CAP) { atomicAdd(&(bar)[XB_TMO], 1u); break; } } } } while (0)
; __device__ __forceinline__ void xcd_barrier(const XcdBarrier& b) {
;     asm volatile("s_waitcnt vmcnt(0)" ::: "memory");
;     __syncthreads();
;     if (threadIdx.x == 0) {
;         unsigned* bar = b.bar;
;         __builtin_amdgcn_s_waitcnt(0);
;         unsigned nloc = b.st[0], nx = b.st[1];
;         if (nloc == 0u) { xcd_barrier_complete(bar, b.x, nloc, nx); b.st[0] = nloc; b.st[1] = nx; }
;         const unsigned old = xb_add(&bar[XB_XSUB(b.x)], 1u);
;         const unsigned gen = old / nloc;
;         if (old + 1u == (gen + 1u) * nloc) {
;             __builtin_amdgcn_fence(__ATOMIC_RELEASE, "agent");
;             asm volatile("s_waitcnt vmcnt(0)" ::: "memory");
;             const unsigned og = xb_add(&bar[XB_TOP], 1u);
;             const unsigned tg = og / nx;
;             if (og + 1u == (tg + 1u) * nx) xb_add(&bar[XB_TOPGEN], 1u);
;             else XB_SPIN(xb_ld(&bar[XB_TOPGEN]) == tg, bar);
;             __builtin_amdgcn_fence(__ATOMIC_ACQUIRE, "agent");
;             xb_add(&bar[XB_XGEN(b.x)], 1u);
;             asm volatile("s_waitcnt vmcnt(0)" ::: "memory");
;         } else {
;             XB_SPIN(xb_ld(&bar[XB_XGEN(b.x)]) == gen, bar);
;             __builtin_amdgcn_fence(__ATOMIC_ACQUIRE, "agent");
;             asm volatile("s_waitcnt vmcnt(0)" ::: "memory");
;         }
;     }
;     __syncthreads();
; }
.LBB0_385:
	s_cmp_gt_i32 s85, 3
	s_cselect_b64 s[2:3], -1, 0
	s_and_b64 s[0:1], s[4:5], s[2:3]
	s_andn2_b64 vcc, exec, s[0:1]
	s_cbranch_vccnz .LBB0_439
	s_waitcnt vmcnt(0) lgkmcnt(0)
	s_barrier
	s_mov_b64 s[4:5], exec
	v_readlane_b32 s0, v248, 1
	v_readlane_b32 s1, v248, 2
	s_and_b64 s[0:1], s[4:5], s[0:1]
	s_mov_b64 exec, s[0:1]
	s_cbranch_execz .LBB0_438
	s_add_i32 s0, 0, 0x20000
	v_mov_b32_e32 v0, s0
	ds_read_b32 v2, v0
	ds_read_b32 v3, v0 offset:4
	v_readlane_b32 s6, v248, 5
	v_readlane_b32 s8, v248, 3
	v_readlane_b32 s9, v248, 4
	s_lshl_b32 s6, s6, 8
	s_add_u32 s6, s8, s6
	s_addc_u32 s7, s9, 0
	v_mov_b32_e32 v4, 0x1000
	v_mov_b32_e32 v1, 1
	s_nop 4
	global_atomic_add v5, v4, v1, s[6:7] offset:1024 sc0
	s_waitcnt vmcnt(0) lgkmcnt(0)
	v_readfirstlane_b32 s10, v5
	v_readfirstlane_b32 s11, v2
	v_readfirstlane_b32 s12, v3
	s_nop 3
	s_add_u32 s10, s10, 1
	s_mul_i32 s11, s11, 3
	s_mul_i32 s12, s12, 3
	s_cmp_lg_u32 s10, s11
	s_cbranch_scc1 .Lnb_wait_2
	buffer_wbl2 sc1
	s_waitcnt vmcnt(0)
	v_mov_b32_e32 v4, 0xbed7000
	global_atomic_add v4, v1, s[50:51] offset:1024

; __device__ __forceinline__ unsigned xb_ld(unsigned* p)              { return __hip_atomic_load(p, __ATOMIC_RELAXED, __HIP_MEMORY_SCOPE_AGENT); }
; __device__ __forceinline__ unsigned xb_add(unsigned* p, unsigned v) { return __hip_atomic_fetch_add(p, v, __ATOMIC_RELAXED, __HIP_MEMORY_SCOPE_AGENT); }
; #define XB_SPIN(cond, bar) do { unsigned _sp = 0; while (cond) { __builtin_amdgcn_s_sleep(1); \
;     if ((++_sp & 255u) == 0u) { if (xb_ld(&(bar)[XB_TMO])) break; if (_sp > XB_SPIN_CAP) { atomicAdd(&(bar)[XB_TMO], 1u); break; } } } } while (0)
; __device__ __forceinline__ void xcd_barrier(const XcdBarrier& b) {
;     asm volatile("s_waitcnt vmcnt(0)" ::: "memory");
;     __syncthreads();
;     if (threadIdx.x == 0) {
;         unsigned* bar = b.bar;
;         __builtin_amdgcn_s_waitcnt(0);
;         unsigned nloc = b.st[0], nx = b.st[1];
;         if (nloc == 0u) { xcd_barrier_complete(bar, b.x, nloc, nx); b.st[0] = nloc; b.st[1] = nx; }
;         const unsigned old = xb_add(&bar[XB_XSUB(b.x)], 1u);
;         const unsigned gen = old / nloc;
;         if (old + 1u == (gen + 1u) * nloc) {
;             __builtin_amdgcn_fence(__ATOMIC_RELEASE, "agent");
;             asm volatile("s_waitcnt vmcnt(0)" ::: "memory");
;             const unsigned og = xb_add(&bar[XB_TOP], 1u);
;             const unsigned tg = og / nx;
;             if (og + 1u == (tg + 1u) * nx) xb_add(&bar[XB_TOPGEN], 1u);
;             else XB_SPIN(xb_ld(&bar[XB_TOPGEN]) == tg, bar);
;             __builtin_amdgcn_fence(__ATOMIC_ACQUIRE, "agent");
;             xb_add(&bar[XB_XGEN(b.x)], 1u);
;             asm volatile("s_waitcnt vmcnt(0)" ::: "memory");
;         } else {
;             XB_SPIN(xb_ld(&bar[XB_XGEN(b.x)]) == gen, bar);
;             __builtin_amdgcn_fence(__ATOMIC_ACQUIRE, "agent");
;             asm volatile("s_waitcnt vmcnt(0)" ::: "memory");
;         }
;     }
;     __syncthreads();
; }
.LBB0_605:
	s_cmp_gt_i32 s85, 4
	s_cselect_b64 s[2:3], -1, 0
	s_and_b64 s[0:1], s[12:13], s[2:3]
	s_andn2_b64 vcc, exec, s[0:1]
	s_cbranch_vccnz .LBB0_659
	s_waitcnt vmcnt(0) lgkmcnt(0)
	s_barrier
	s_mov_b64 s[4:5], exec
	v_readlane_b32 s0, v248, 1
	v_readlane_b32 s1, v248, 2
	s_and_b64 s[0:1], s[4:5], s[0:1]
	s_mov_b64 exec, s[0:1]
	s_cbranch_execz .LBB0_658
	s_add_i32 s0, 0, 0x20000
	v_mov_b32_e32 v0, s0
	ds_read_b32 v2, v0
	ds_read_b32 v3, v0 offset:4
	v_readlane_b32 s6, v248, 5
	v_readlane_b32 s8, v248, 3
	v_readlane_b32 s9, v248, 4
	s_lshl_b32 s6, s6, 8
	s_add_u32 s6, s8, s6
	s_addc_u32 s7, s9, 0
	v_mov_b32_e32 v4, 0x1000
	v_mov_b32_e32 v1, 1
	s_nop 4
	global_atomic_add v5, v4, v1, s[6:7] offset:1024 sc0
	s_waitcnt vmcnt(0) lgkmcnt(0)
	v_readfirstlane_b32 s10, v5
	v_readfirstlane_b32 s11, v2
	v_readfirstlane_b32 s12, v3
	s_nop 3
	s_add_u32 s10, s10, 1
	s_mul_i32 s11, s11, 4
	s_mul_i32 s12, s12, 4
	s_cmp_lg_u32 s10, s11
	s_cbranch_scc1 .Lnb_wait_3
	buffer_wbl2 sc1
	s_waitcnt vmcnt(0)
	v_mov_b32_e32 v4, 0xbed7000
	global_atomic_add v4, v1, s[50:51] offset:1024

; __device__ __forceinline__ unsigned xb_ld(unsigned* p)              { return __hip_atomic_load(p, __ATOMIC_RELAXED, __HIP_MEMORY_SCOPE_AGENT); }
; __device__ __forceinline__ unsigned xb_add(unsigned* p, unsigned v) { return __hip_atomic_fetch_add(p, v, __ATOMIC_RELAXED, __HIP_MEMORY_SCOPE_AGENT); }
; #define XB_SPIN(cond, bar) do { unsigned _sp = 0; while (cond) { __builtin_amdgcn_s_sleep(1); \
;     if ((++_sp & 255u) == 0u) { if (xb_ld(&(bar)[XB_TMO])) break; if (_sp > XB_SPIN_CAP) { atomicAdd(&(bar)[XB_TMO], 1u); break; } } } } while (0)
; __device__ __forceinline__ void xcd_barrier(const XcdBarrier& b) {
;     asm volatile("s_waitcnt vmcnt(0)" ::: "memory");
;     __syncthreads();
;     if (threadIdx.x == 0) {
;         unsigned* bar = b.bar;
;         __builtin_amdgcn_s_waitcnt(0);
;         unsigned nloc = b.st[0], nx = b.st[1];
;         if (nloc == 0u) { xcd_barrier_complete(bar, b.x, nloc, nx); b.st[0] = nloc; b.st[1] = nx; }
;         const unsigned old = xb_add(&bar[XB_XSUB(b.x)], 1u);
;         const unsigned gen = old / nloc;
;         if (old + 1u == (gen + 1u) * nloc) {
;             __builtin_amdgcn_fence(__ATOMIC_RELEASE, "agent");
;             asm volatile("s_waitcnt vmcnt(0)" ::: "memory");
;             const unsigned og = xb_add(&bar[XB_TOP], 1u);
;             const unsigned tg = og / nx;
;             if (og + 1u == (tg + 1u) * nx) xb_add(&bar[XB_TOPGEN], 1u);
;             else XB_SPIN(xb_ld(&bar[XB_TOPGEN]) == tg, bar);
;             __builtin_amdgcn_fence(__ATOMIC_ACQUIRE, "agent");
;             xb_add(&bar[XB_XGEN(b.x)], 1u);
;             asm volatile("s_waitcnt vmcnt(0)" ::: "memory");
;         } else {
;             XB_SPIN(xb_ld(&bar[XB_XGEN(b.x)]) == gen, bar);
;             __builtin_amdgcn_fence(__ATOMIC_ACQUIRE, "agent");
;             asm volatile("s_waitcnt vmcnt(0)" ::: "memory");
;         }
;     }
;     __syncthreads();
; }
.LBB0_670:
	s_cmp_gt_i32 s85, 5
	s_cselect_b64 s[2:3], -1, 0
	s_and_b64 s[0:1], s[8:9], s[2:3]
	s_andn2_b64 vcc, exec, s[0:1]
	s_cbranch_vccnz .LBB0_724
	s_waitcnt vmcnt(0) lgkmcnt(0)
	s_barrier
	s_mov_b64 s[4:5], exec
	v_readlane_b32 s0, v248, 1
	v_readlane_b32 s1, v248, 2
	s_and_b64 s[0:1], s[4:5], s[0:1]
	s_mov_b64 exec, s[0:1]
	s_cbranch_execz .LBB0_723
	s_add_i32 s0, 0, 0x20000
	v_mov_b32_e32 v0, s0
	ds_read_b32 v2, v0
	ds_read_b32 v3, v0 offset:4
	v_readlane_b32 s6, v248, 5
	v_readlane_b32 s8, v248, 3
	v_readlane_b32 s9, v248, 4
	s_lshl_b32 s6, s6, 8
	s_add_u32 s6, s8, s6
	s_addc_u32 s7, s9, 0
	v_mov_b32_e32 v4, 0x1000
	v_mov_b32_e32 v1, 1
	s_nop 4
	global_atomic_add v5, v4, v1, s[6:7] offset:1024 sc0
	s_waitcnt vmcnt(0) lgkmcnt(0)
	v_readfirstlane_b32 s10, v5
	v_readfirstlane_b32 s11, v2
	v_readfirstlane_b32 s12, v3
	s_nop 3
	s_add_u32 s10, s10, 1
	s_mul_i32 s11, s11, 5
	s_mul_i32 s12, s12, 5
	s_cmp_lg_u32 s10, s11
	s_cbranch_scc1 .Lnb_wait_4
	buffer_wbl2 sc1
	s_waitcnt vmcnt(0)
	v_mov_b32_e32 v4, 0xbed7000
	global_atomic_add v4, v1, s[50:51] offset:1024

; __device__ __forceinline__ unsigned xb_ld(unsigned* p)              { return __hip_atomic_load(p, __ATOMIC_RELAXED, __HIP_MEMORY_SCOPE_AGENT); }
; __device__ __forceinline__ unsigned xb_add(unsigned* p, unsigned v) { return __hip_atomic_fetch_add(p, v, __ATOMIC_RELAXED, __HIP_MEMORY_SCOPE_AGENT); }
; #define XB_SPIN(cond, bar) do { unsigned _sp = 0; while (cond) { __builtin_amdgcn_s_sleep(1); \
;     if ((++_sp & 255u) == 0u) { if (xb_ld(&(bar)[XB_TMO])) break; if (_sp > XB_SPIN_CAP) { atomicAdd(&(bar)[XB_TMO], 1u); break; } } } } while (0)
; __device__ __forceinline__ void xcd_barrier(const XcdBarrier& b) {
;     asm volatile("s_waitcnt vmcnt(0)" ::: "memory");
;     __syncthreads();
;     if (threadIdx.x == 0) {
;         unsigned* bar = b.bar;
;         __builtin_amdgcn_s_waitcnt(0);
;         unsigned nloc = b.st[0], nx = b.st[1];
;         if (nloc == 0u) { xcd_barrier_complete(bar, b.x, nloc, nx); b.st[0] = nloc; b.st[1] = nx; }
;         const unsigned old = xb_add(&bar[XB_XSUB(b.x)], 1u);
;         const unsigned gen = old / nloc;
;         if (old + 1u == (gen + 1u) * nloc) {
;             __builtin_amdgcn_fence(__ATOMIC_RELEASE, "agent");
;             asm volatile("s_waitcnt vmcnt(0)" ::: "memory");
;             const unsigned og = xb_add(&bar[XB_TOP], 1u);
;             const unsigned tg = og / nx;
;             if (og + 1u == (tg + 1u) * nx) xb_add(&bar[XB_TOPGEN], 1u);
;             else XB_SPIN(xb_ld(&bar[XB_TOPGEN]) == tg, bar);
;             __builtin_amdgcn_fence(__ATOMIC_ACQUIRE, "agent");
;             xb_add(&bar[XB_XGEN(b.x)], 1u);
;             asm volatile("s_waitcnt vmcnt(0)" ::: "memory");
;         } else {
;             XB_SPIN(xb_ld(&bar[XB_XGEN(b.x)]) == gen, bar);
;             __builtin_amdgcn_fence(__ATOMIC_ACQUIRE, "agent");
;             asm volatile("s_waitcnt vmcnt(0)" ::: "memory");
;         }
;     }
;     __syncthreads();
; }
.LBB0_778:
	s_cmp_gt_i32 s84, 6
	s_cselect_b64 s[0:1], -1, 0
	s_cmp_gt_i32 s85, 7
	s_cselect_b64 s[2:3], -1, 0
	s_cmp_lt_i32 s85, 8
	s_cselect_b64 s[4:5], -1, 0
	s_or_b64 s[0:1], s[0:1], s[4:5]
	s_and_b64 vcc, exec, s[0:1]
	s_cbranch_vccnz .LBB0_832
	s_waitcnt vmcnt(0) lgkmcnt(0)
	s_barrier
	s_mov_b64 s[4:5], exec
	v_readlane_b32 s0, v248, 1
	v_readlane_b32 s1, v248, 2
	s_and_b64 s[0:1], s[4:5], s[0:1]
	s_mov_b64 exec, s[0:1]
	s_cbranch_execz .LBB0_831
	s_add_i32 s0, 0, 0x20000
	v_mov_b32_e32 v0, s0
	ds_read_b32 v2, v0
	ds_read_b32 v3, v0 offset:4
	v_readlane_b32 s6, v248, 5
	v_readlane_b32 s8, v248, 3
	v_readlane_b32 s9, v248, 4
	s_lshl_b32 s6, s6, 8
	s_add_u32 s6, s8, s6
	s_addc_u32 s7, s9, 0
	v_mov_b32_e32 v4, 0x1000
	v_mov_b32_e32 v1, 1
	s_nop 4
	global_atomic_add v5, v4, v1, s[6:7] offset:1024 sc0
	s_waitcnt vmcnt(0) lgkmcnt(0)
	v_readfirstlane_b32 s10, v5
	v_readfirstlane_b32 s11, v2
	v_readfirstlane_b32 s12, v3
	s_nop 3
	s_add_u32 s10, s10, 1
	s_mul_i32 s11, s11, 6
	s_mul_i32 s12, s12, 6
	s_cmp_lg_u32 s10, s11
	s_cbranch_scc1 .Lnb_wait_5
	buffer_wbl2 sc1
	s_waitcnt vmcnt(0)
	v_mov_b32_e32 v4, 0xbed7000
	global_atomic_add v4, v1, s[50:51] offset:1024

; __device__ __forceinline__ unsigned xb_ld(unsigned* p)              { return __hip_atomic_load(p, __ATOMIC_RELAXED, __HIP_MEMORY_SCOPE_AGENT); }
; __device__ __forceinline__ unsigned xb_add(unsigned* p, unsigned v) { return __hip_atomic_fetch_add(p, v, __ATOMIC_RELAXED, __HIP_MEMORY_SCOPE_AGENT); }
; #define XB_SPIN(cond, bar) do { unsigned _sp = 0; while (cond) { __builtin_amdgcn_s_sleep(1); \
;     if ((++_sp & 255u) == 0u) { if (xb_ld(&(bar)[XB_TMO])) break; if (_sp > XB_SPIN_CAP) { atomicAdd(&(bar)[XB_TMO], 1u); break; } } } } while (0)
; __device__ __forceinline__ void xcd_barrier(const XcdBarrier& b) {
;     asm volatile("s_waitcnt vmcnt(0)" ::: "memory");
;     __syncthreads();
;     if (threadIdx.x == 0) {
;         unsigned* bar = b.bar;
;         __builtin_amdgcn_s_waitcnt(0);
;         unsigned nloc = b.st[0], nx = b.st[1];
;         if (nloc == 0u) { xcd_barrier_complete(bar, b.x, nloc, nx); b.st[0] = nloc; b.st[1] = nx; }
;         const unsigned old = xb_add(&bar[XB_XSUB(b.x)], 1u);
;         const unsigned gen = old / nloc;
;         if (old + 1u == (gen + 1u) * nloc) {
;             __builtin_amdgcn_fence(__ATOMIC_RELEASE, "agent");
;             asm volatile("s_waitcnt vmcnt(0)" ::: "memory");
;             const unsigned og = xb_add(&bar[XB_TOP], 1u);
;             const unsigned tg = og / nx;
;             if (og + 1u == (tg + 1u) * nx) xb_add(&bar[XB_TOPGEN], 1u);
;             else XB_SPIN(xb_ld(&bar[XB_TOPGEN]) == tg, bar);
;             __builtin_amdgcn_fence(__ATOMIC_ACQUIRE, "agent");
;             xb_add(&bar[XB_XGEN(b.x)], 1u);
;             asm volatile("s_waitcnt vmcnt(0)" ::: "memory");
;         } else {
;             XB_SPIN(xb_ld(&bar[XB_XGEN(b.x)]) == gen, bar);
;             __builtin_amdgcn_fence(__ATOMIC_ACQUIRE, "agent");
;             asm volatile("s_waitcnt vmcnt(0)" ::: "memory");
;         }
;     }
;     __syncthreads();
; }
.LBB0_938:
	s_cmp_gt_i32 s85, 8
	s_cselect_b64 s[2:3], -1, 0
	s_and_b64 s[0:1], s[10:11], s[2:3]
	s_andn2_b64 vcc, exec, s[0:1]
	s_cbranch_vccnz .LBB0_992
	s_waitcnt vmcnt(0) lgkmcnt(0)
	s_barrier
	s_mov_b64 s[4:5], exec
	v_readlane_b32 s0, v248, 1
	v_readlane_b32 s1, v248, 2
	s_and_b64 s[0:1], s[4:5], s[0:1]
	s_mov_b64 exec, s[0:1]
	s_cbranch_execz .LBB0_991
	s_add_i32 s0, 0, 0x20000
	v_mov_b32_e32 v0, s0
	ds_read_b32 v2, v0
	ds_read_b32 v3, v0 offset:4
	v_readlane_b32 s6, v248, 5
	v_readlane_b32 s8, v248, 3
	v_readlane_b32 s9, v248, 4
	s_lshl_b32 s6, s6, 8
	s_add_u32 s6, s8, s6
	s_addc_u32 s7, s9, 0
	v_mov_b32_e32 v4, 0x1000
	v_mov_b32_e32 v1, 1
	s_nop 4
	global_atomic_add v5, v4, v1, s[6:7] offset:1024 sc0
	s_waitcnt vmcnt(0) lgkmcnt(0)
	v_readfirstlane_b32 s10, v5
	v_readfirstlane_b32 s11, v2
	v_readfirstlane_b32 s12, v3
	s_nop 3
	s_add_u32 s10, s10, 1
	s_mul_i32 s11, s11, 7
	s_mul_i32 s12, s12, 7
	s_cmp_lg_u32 s10, s11
	s_cbranch_scc1 .Lnb_wait_6
	buffer_wbl2 sc1
	s_waitcnt vmcnt(0)
	v_mov_b32_e32 v4, 0xbed7000
	global_atomic_add v4, v1, s[50:51] offset:1024

; __device__ __forceinline__ unsigned xb_ld(unsigned* p)              { return __hip_atomic_load(p, __ATOMIC_RELAXED, __HIP_MEMORY_SCOPE_AGENT); }
; __device__ __forceinline__ unsigned xb_add(unsigned* p, unsigned v) { return __hip_atomic_fetch_add(p, v, __ATOMIC_RELAXED, __HIP_MEMORY_SCOPE_AGENT); }
; #define XB_SPIN(cond, bar) do { unsigned _sp = 0; while (cond) { __builtin_amdgcn_s_sleep(1); \
;     if ((++_sp & 255u) == 0u) { if (xb_ld(&(bar)[XB_TMO])) break; if (_sp > XB_SPIN_CAP) { atomicAdd(&(bar)[XB_TMO], 1u); break; } } } } while (0)
; __device__ __forceinline__ void xcd_barrier(const XcdBarrier& b) {
;     asm volatile("s_waitcnt vmcnt(0)" ::: "memory");
;     __syncthreads();
;     if (threadIdx.x == 0) {
;         unsigned* bar = b.bar;
;         __builtin_amdgcn_s_waitcnt(0);
;         unsigned nloc = b.st[0], nx = b.st[1];
;         if (nloc == 0u) { xcd_barrier_complete(bar, b.x, nloc, nx); b.st[0] = nloc; b.st[1] = nx; }
;         const unsigned old = xb_add(&bar[XB_XSUB(b.x)], 1u);
;         const unsigned gen = old / nloc;
;         if (old + 1u == (gen + 1u) * nloc) {
;             __builtin_amdgcn_fence(__ATOMIC_RELEASE, "agent");
;             asm volatile("s_waitcnt vmcnt(0)" ::: "memory");
;             const unsigned og = xb_add(&bar[XB_TOP], 1u);
;             const unsigned tg = og / nx;
;             if (og + 1u == (tg + 1u) * nx) xb_add(&bar[XB_TOPGEN], 1u);
;             else XB_SPIN(xb_ld(&bar[XB_TOPGEN]) == tg, bar);
;             __builtin_amdgcn_fence(__ATOMIC_ACQUIRE, "agent");
;             xb_add(&bar[XB_XGEN(b.x)], 1u);
;             asm volatile("s_waitcnt vmcnt(0)" ::: "memory");
;         } else {
;             XB_SPIN(xb_ld(&bar[XB_XGEN(b.x)]) == gen, bar);
;             __builtin_amdgcn_fence(__ATOMIC_ACQUIRE, "agent");
;             asm volatile("s_waitcnt vmcnt(0)" ::: "memory");
;         }
;     }
;     __syncthreads();
; }
.LBB0_1315:
	s_cmp_gt_i32 s85, 9
	s_cselect_b64 s[2:3], -1, 0
	s_and_b64 s[0:1], s[6:7], s[2:3]
	s_andn2_b64 vcc, exec, s[0:1]
	s_cbranch_vccnz .LBB0_1369
	s_waitcnt vmcnt(0) lgkmcnt(0)
	s_barrier
	s_mov_b64 s[4:5], exec
	v_readlane_b32 s0, v248, 1
	v_readlane_b32 s1, v248, 2
	s_and_b64 s[0:1], s[4:5], s[0:1]
	s_mov_b64 exec, s[0:1]
	s_cbranch_execz .LBB0_1368
	s_add_i32 s0, 0, 0x20000
	v_mov_b32_e32 v0, s0
	ds_read_b32 v2, v0
	ds_read_b32 v3, v0 offset:4
	v_readlane_b32 s6, v248, 5
	v_readlane_b32 s8, v248, 3
	v_readlane_b32 s9, v248, 4
	s_lshl_b32 s6, s6, 8
	s_add_u32 s6, s8, s6
	s_addc_u32 s7, s9, 0
	v_mov_b32_e32 v4, 0x1000
	v_mov_b32_e32 v1, 1
	s_nop 4
	global_atomic_add v5, v4, v1, s[6:7] offset:1024 sc0
	s_waitcnt vmcnt(0) lgkmcnt(0)
	v_readfirstlane_b32 s10, v5
	v_readfirstlane_b32 s11, v2
	v_readfirstlane_b32 s12, v3
	s_nop 3
	s_add_u32 s10, s10, 1
	s_mul_i32 s11, s11, 8
	s_mul_i32 s12, s12, 8
	s_cmp_lg_u32 s10, s11
	s_cbranch_scc1 .Lnb_wait_7
	buffer_wbl2 sc1
	s_waitcnt vmcnt(0)
	v_mov_b32_e32 v4, 0xbed7000
	global_atomic_add v4, v1, s[50:51] offset:1024

; __device__ __forceinline__ unsigned xb_ld(unsigned* p)              { return __hip_atomic_load(p, __ATOMIC_RELAXED, __HIP_MEMORY_SCOPE_AGENT); }
; __device__ __forceinline__ unsigned xb_add(unsigned* p, unsigned v) { return __hip_atomic_fetch_add(p, v, __ATOMIC_RELAXED, __HIP_MEMORY_SCOPE_AGENT); }
; #define XB_SPIN(cond, bar) do { unsigned _sp = 0; while (cond) { __builtin_amdgcn_s_sleep(1); \
;     if ((++_sp & 255u) == 0u) { if (xb_ld(&(bar)[XB_TMO])) break; if (_sp > XB_SPIN_CAP) { atomicAdd(&(bar)[XB_TMO], 1u); break; } } } } while (0)
; __device__ __forceinline__ void xcd_barrier(const XcdBarrier& b) {
;     asm volatile("s_waitcnt vmcnt(0)" ::: "memory");
;     __syncthreads();
;     if (threadIdx.x == 0) {
;         unsigned* bar = b.bar;
;         __builtin_amdgcn_s_waitcnt(0);
;         unsigned nloc = b.st[0], nx = b.st[1];
;         if (nloc == 0u) { xcd_barrier_complete(bar, b.x, nloc, nx); b.st[0] = nloc; b.st[1] = nx; }
;         const unsigned old = xb_add(&bar[XB_XSUB(b.x)], 1u);
;         const unsigned gen = old / nloc;
;         if (old + 1u == (gen + 1u) * nloc) {
;             __builtin_amdgcn_fence(__ATOMIC_RELEASE, "agent");
;             asm volatile("s_waitcnt vmcnt(0)" ::: "memory");
;             const unsigned og = xb_add(&bar[XB_TOP], 1u);
;             const unsigned tg = og / nx;
;             if (og + 1u == (tg + 1u) * nx) xb_add(&bar[XB_TOPGEN], 1u);
;             else XB_SPIN(xb_ld(&bar[XB_TOPGEN]) == tg, bar);
;             __builtin_amdgcn_fence(__ATOMIC_ACQUIRE, "agent");
;             xb_add(&bar[XB_XGEN(b.x)], 1u);
;             asm volatile("s_waitcnt vmcnt(0)" ::: "memory");
;         } else {
;             XB_SPIN(xb_ld(&bar[XB_XGEN(b.x)]) == gen, bar);
;             __builtin_amdgcn_fence(__ATOMIC_ACQUIRE, "agent");
;             asm volatile("s_waitcnt vmcnt(0)" ::: "memory");
;         }
;     }
;     __syncthreads();
; }
.LBB0_1401:
	s_cmp_gt_i32 s85, 10
	s_cselect_b64 s[2:3], -1, 0
	s_and_b64 s[0:1], s[4:5], s[2:3]
	s_andn2_b64 vcc, exec, s[0:1]
	s_cbranch_vccnz .LBB0_1455
	s_waitcnt vmcnt(0) lgkmcnt(0)
	s_barrier
	s_mov_b64 s[4:5], exec
	v_readlane_b32 s0, v248, 1
	v_readlane_b32 s1, v248, 2
	s_and_b64 s[0:1], s[4:5], s[0:1]
	s_mov_b64 exec, s[0:1]
	s_cbranch_execz .LBB0_1454
	s_add_i32 s0, 0, 0x20000
	v_mov_b32_e32 v0, s0
	ds_read_b32 v2, v0
	ds_read_b32 v3, v0 offset:4
	v_readlane_b32 s6, v248, 5
	v_readlane_b32 s8, v248, 3
	v_readlane_b32 s9, v248, 4
	s_lshl_b32 s6, s6, 8
	s_add_u32 s6, s8, s6
	s_addc_u32 s7, s9, 0
	v_mov_b32_e32 v4, 0x1000
	v_mov_b32_e32 v1, 1
	s_nop 4
	global_atomic_add v5, v4, v1, s[6:7] offset:1024 sc0
	s_waitcnt vmcnt(0) lgkmcnt(0)
	v_readfirstlane_b32 s10, v5
	v_readfirstlane_b32 s11, v2
	v_readfirstlane_b32 s12, v3
	s_nop 3
	s_add_u32 s10, s10, 1
	s_mul_i32 s11, s11, 9
	s_mul_i32 s12, s12, 9
	s_cmp_lg_u32 s10, s11
	s_cbranch_scc1 .Lnb_wait_8
	buffer_wbl2 sc1
	s_waitcnt vmcnt(0)
	v_mov_b32_e32 v4, 0xbed7000
	global_atomic_add v4, v1, s[50:51] offset:1024
